# DeltaNet prep S5 (transposed-output MFMAs, dwordx2 stores): stores of row tile k-1 issued right after the MFMAs of tile k instead of all at the end
# baseline (speedup 1.0000x reference)
.Lsv_b14:
	v_fmac_f32_e32 v108, v212, v106
	v_fmac_f32_e32 v109, v220, v106
	v_fmac_f32_e32 v110, v228, v106
	v_fmac_f32_e32 v111, v236, v106
	s_waitcnt lgkmcnt(0)
	ds_read_b128 v[176:179], v128 offset:15360
	ds_read_b128 v[180:183], v128 offset:15376
	ds_read_b128 v[184:187], v128 offset:15616
	ds_read_b128 v[188:191], v128 offset:15632
	ds_read_b128 v[192:195], v128 offset:15872
	ds_read_b128 v[196:199], v128 offset:15888
	ds_read_b128 v[200:203], v128 offset:16128
	ds_read_b128 v[238:241], v128 offset:16144
	ds_read_b32 v146, v129 offset:15772
	ds_read_b32 v147, v129 offset:16028
	ds_read_b32 v148, v129 offset:16060
	ds_read_b32 v149, v129 offset:16284
	ds_read_b32 v150, v129 offset:16316
	ds_read_b32 v151, v129 offset:16348
	v_add_f32_dpp v108, v108, v108 quad_perm:[1,0,3,2] row_mask:0xf bank_mask:0xf bound_ctrl:1
	v_add_f32_dpp v109, v109, v109 quad_perm:[1,0,3,2] row_mask:0xf bank_mask:0xf bound_ctrl:1
	v_cmp_eq_u32_e32 vcc, 60, v0
	v_add_f32_dpp v110, v110, v110 quad_perm:[1,0,3,2] row_mask:0xf bank_mask:0xf bound_ctrl:1
	v_add_f32_dpp v111, v111, v111 quad_perm:[1,0,3,2] row_mask:0xf bank_mask:0xf bound_ctrl:1
	v_cndmask_b32_e64 v120, 0, 1.0, vcc
	v_cmp_eq_u32_e32 vcc, 61, v0
	v_add_f32_dpp v108, v108, v108 quad_perm:[2,3,0,1] row_mask:0xf bank_mask:0xf bound_ctrl:1
	v_add_f32_dpp v109, v109, v109 quad_perm:[2,3,0,1] row_mask:0xf bank_mask:0xf bound_ctrl:1
	v_cndmask_b32_e64 v121, 0, 1.0, vcc
	v_cmp_eq_u32_e32 vcc, 62, v0
	v_add_f32_dpp v110, v110, v110 quad_perm:[2,3,0,1] row_mask:0xf bank_mask:0xf bound_ctrl:1
	v_add_f32_dpp v111, v111, v111 quad_perm:[2,3,0,1] row_mask:0xf bank_mask:0xf bound_ctrl:1
	v_cndmask_b32_e64 v122, 0, 1.0, vcc
	v_cmp_eq_u32_e32 vcc, 63, v0
	v_add_f32_dpp v108, v108, v108 row_half_mirror row_mask:0xf bank_mask:0xf bound_ctrl:1
	v_add_f32_dpp v109, v109, v109 row_half_mirror row_mask:0xf bank_mask:0xf bound_ctrl:1
	v_cndmask_b32_e64 v123, 0, 1.0, vcc
	v_add_f32_dpp v110, v110, v110 row_half_mirror row_mask:0xf bank_mask:0xf bound_ctrl:1
	v_add_f32_dpp v111, v111, v111 row_half_mirror row_mask:0xf bank_mask:0xf bound_ctrl:1
	v_sub_f32_e32 v124, v116, v108
	v_sub_f32_e32 v125, v117, v109
	v_sub_f32_e32 v126, v118, v110
	v_sub_f32_e32 v127, v119, v111
	v_fma_f32 v125, -v130, v124, v125
	v_fma_f32 v126, -v131, v124, v126
	v_fma_f32 v127, -v133, v124, v127
	s_waitcnt lgkmcnt(13)
	v_mul_f32_e32 v112, v176, v100
	s_waitcnt lgkmcnt(11)
	v_mul_f32_e32 v113, v184, v100
	v_fma_f32 v126, -v132, v125, v126
	v_fma_f32 v127, -v134, v125, v127
	s_waitcnt lgkmcnt(9)
	v_mul_f32_e32 v114, v192, v100
	s_waitcnt lgkmcnt(7)
	v_mul_f32_e32 v115, v200, v100
	v_fma_f32 v127, -v135, v126, v127
	v_fmac_f32_e32 v112, v177, v101
	v_fmac_f32_e32 v113, v185, v101
	v_cndmask_b32_e64 v107, v107, v124, s[6:7]
	v_fmac_f32_e32 v114, v193, v101
	v_cndmask_b32_e64 v107, v107, v125, s[8:9]
	v_fmac_f32_e32 v115, v201, v101
	v_cndmask_b32_e64 v107, v107, v126, s[10:11]
	v_fmac_f32_e32 v112, v178, v102
	v_cndmask_b32_e64 v107, v107, v127, s[12:13]
	v_fmac_f32_e32 v113, v186, v102
	v_fmac_f32_e32 v114, v194, v102
	v_fmac_f32_e32 v115, v202, v102
	v_fmac_f32_e32 v112, v179, v103
	v_fmac_f32_e32 v113, v187, v103
	v_fmac_f32_e32 v114, v195, v103
	v_fmac_f32_e32 v115, v203, v103
	v_fmac_f32_e32 v112, v180, v104
	v_fmac_f32_e32 v113, v188, v104
	v_fmac_f32_e32 v114, v196, v104
	s_waitcnt lgkmcnt(6)
	v_fmac_f32_e32 v115, v238, v104
	v_fmac_f32_e32 v112, v181, v105
	v_fmac_f32_e32 v113, v189, v105
	v_fmac_f32_e32 v114, v197, v105
	v_fmac_f32_e32 v115, v239, v105
	v_fmac_f32_e32 v112, v182, v106
	v_fmac_f32_e32 v113, v190, v106
	v_fmac_f32_e32 v114, v198, v106
	v_fmac_f32_e32 v115, v240, v106
	v_fmac_f32_e32 v112, v183, v107
	v_fmac_f32_e32 v113, v191, v107
	v_fmac_f32_e32 v114, v199, v107
	v_fmac_f32_e32 v115, v241, v107
	v_add_f32_dpp v112, v112, v112 quad_perm:[1,0,3,2] row_mask:0xf bank_mask:0xf bound_ctrl:1
	v_add_f32_dpp v113, v113, v113 quad_perm:[1,0,3,2] row_mask:0xf bank_mask:0xf bound_ctrl:1
	v_add_f32_dpp v114, v114, v114 quad_perm:[1,0,3,2] row_mask:0xf bank_mask:0xf bound_ctrl:1
	v_add_f32_dpp v115, v115, v115 quad_perm:[1,0,3,2] row_mask:0xf bank_mask:0xf bound_ctrl:1
	v_add_f32_dpp v112, v112, v112 quad_perm:[2,3,0,1] row_mask:0xf bank_mask:0xf bound_ctrl:1
	v_add_f32_dpp v113, v113, v113 quad_perm:[2,3,0,1] row_mask:0xf bank_mask:0xf bound_ctrl:1
	v_add_f32_dpp v114, v114, v114 quad_perm:[2,3,0,1] row_mask:0xf bank_mask:0xf bound_ctrl:1
	v_add_f32_dpp v115, v115, v115 quad_perm:[2,3,0,1] row_mask:0xf bank_mask:0xf bound_ctrl:1
	v_add_f32_dpp v112, v112, v112 row_half_mirror row_mask:0xf bank_mask:0xf bound_ctrl:1
	v_add_f32_dpp v113, v113, v113 row_half_mirror row_mask:0xf bank_mask:0xf bound_ctrl:1
	v_add_f32_dpp v114, v114, v114 row_half_mirror row_mask:0xf bank_mask:0xf bound_ctrl:1
	v_add_f32_dpp v115, v115, v115 row_half_mirror row_mask:0xf bank_mask:0xf bound_ctrl:1
	v_sub_f32_e32 v124, v120, v112
	v_sub_f32_e32 v125, v121, v113
	v_sub_f32_e32 v126, v122, v114
	v_sub_f32_e32 v127, v123, v115
	s_waitcnt lgkmcnt(5)
	v_fma_f32 v125, -v146, v124, v125
	s_waitcnt lgkmcnt(4)
	v_fma_f32 v126, -v147, v124, v126
	s_waitcnt lgkmcnt(2)
	v_fma_f32 v127, -v149, v124, v127
	v_fma_f32 v126, -v148, v125, v126
	s_waitcnt lgkmcnt(1)
	v_fma_f32 v127, -v150, v125, v127
	s_waitcnt lgkmcnt(0)
	v_fma_f32 v127, -v151, v126, v127
	v_cndmask_b32_e64 v107, v107, v124, s[14:15]
	v_cndmask_b32_e64 v107, v107, v125, s[16:17]
	v_cndmask_b32_e64 v107, v107, v126, s[18:19]
	v_cndmask_b32_e64 v107, v107, v127, s[20:21]
	v_lshl_add_u32 v152, v0, 2, 0
	v_add_u32_e32 v153, 0x15c00, v152
	v_add_u32_e32 v154, 0x15e00, v152
	v_add_u32_e32 v155, 0x15f00, v152
	ds_read_b32 v153, v153
	ds_read_b32 v154, v154
	ds_read_b32 v155, v155
	v_mul_u32_u24_e32 v156, 0x48, v2
	v_add_lshl_u32 v156, v0, v156, 1
	v_readlane_b32 s6, v244, 27
	v_readlane_b32 s7, v244, 32
	s_lshl_b64 s[8:9], s[36:37], 14
	s_mov_b32 s36, s2
	s_nop 1
	v_add_u32_e32 v157, s6, v156
	v_add_u32_e32 v156, s7, v156
	s_waitcnt lgkmcnt(0)
	v_mul_f32_e32 v154, v153, v154
	v_mul_f32_e32 v154, v154, v155
	v_mul_f32_e32 v158, v100, v153
	v_mul_f32_e32 v159, v100, v154
	v_cvt_pk_bf16_f32 v158, v158, v158
	v_cvt_pk_bf16_f32 v159, v159, v159
	ds_write_b16 v157, v158 offset:0
	ds_write_b16 v156, v159 offset:0
	v_mul_f32_e32 v158, v101, v153
	v_mul_f32_e32 v159, v101, v154
	v_cvt_pk_bf16_f32 v158, v158, v158
	v_cvt_pk_bf16_f32 v159, v159, v159
	ds_write_b16 v157, v158 offset:1152
	ds_write_b16 v156, v159 offset:1152
	v_mul_f32_e32 v158, v102, v153
	v_mul_f32_e32 v159, v102, v154
	v_cvt_pk_bf16_f32 v158, v158, v158
	v_cvt_pk_bf16_f32 v159, v159, v159
	ds_write_b16 v157, v158 offset:2304
	ds_write_b16 v156, v159 offset:2304
	v_mul_f32_e32 v158, v103, v153
	v_mul_f32_e32 v159, v103, v154
	v_cvt_pk_bf16_f32 v158, v158, v158
	v_cvt_pk_bf16_f32 v159, v159, v159
	ds_write_b16 v157, v158 offset:3456
	ds_write_b16 v156, v159 offset:3456
	v_mul_f32_e32 v158, v104, v153
	v_mul_f32_e32 v159, v104, v154
	v_cvt_pk_bf16_f32 v158, v158, v158
	v_cvt_pk_bf16_f32 v159, v159, v159
	ds_write_b16 v157, v158 offset:4608
	ds_write_b16 v156, v159 offset:4608
	v_mul_f32_e32 v158, v105, v153
	v_mul_f32_e32 v159, v105, v154
	v_cvt_pk_bf16_f32 v158, v158, v158
	v_cvt_pk_bf16_f32 v159, v159, v159
	ds_write_b16 v157, v158 offset:5760
	ds_write_b16 v156, v159 offset:5760
	v_mul_f32_e32 v158, v106, v153
	v_mul_f32_e32 v159, v106, v154
	v_cvt_pk_bf16_f32 v158, v158, v158
	v_cvt_pk_bf16_f32 v159, v159, v159
	ds_write_b16 v157, v158 offset:6912
	ds_write_b16 v156, v159 offset:6912
	v_mul_f32_e32 v158, v107, v153
	v_mul_f32_e32 v159, v107, v154
	v_cvt_pk_bf16_f32 v158, v158, v158
	v_cvt_pk_bf16_f32 v159, v159, v159
	ds_write_b16 v157, v158 offset:8064
	ds_write_b16 v156, v159 offset:8064
	v_mul_u32_u24_e32 v0, 0x48, v46
	v_lshlrev_b32_e32 v0, 1, v0
	v_add3_u32 v84, s6, v0, v48
	s_waitcnt lgkmcnt(0)
	s_barrier
	v_lshlrev_b32_e32 v100, 8, v46
	v_lshl_or_b32 v100, v43, 5, v100
	v_lshl_or_b32 v100, v47, 1, v100
	v_lshl_or_b32 v6, v43, 4, v46
	s_movk_i32 s6, 0x90
	v_mul_lo_u32 v6, v6, s6
	v_add3_u32 v56, 0, v6, v48
	v_add3_u32 v0, s7, v0, v48
	s_add_u32 s6, s22, s8
	s_addc_u32 s7, s23, s9
	s_add_u32 s8, s59, s8
	s_addc_u32 s9, s64, s9
	ds_read_b128 v[6:9], v56 offset:35840
	ds_read_b128 v[104:107], v84
	ds_read_b128 v[14:17], v56 offset:35904
	ds_read_b128 v[108:111], v84 offset:64
	ds_read_b128 v[48:51], v56 offset:17408
	ds_read_b128 v[112:115], v0
	ds_read_b128 v[10:13], v56 offset:17472
	ds_read_b128 v[116:119], v0 offset:64
	ds_read_b128 v[120:123], v84 offset:2304
	ds_read_b128 v[124:127], v84 offset:2368
	ds_read_b128 v[128:131], v0 offset:2304
	ds_read_b128 v[132:135], v0 offset:2368
	ds_read_b128 v[176:179], v84 offset:4608
	ds_read_b128 v[180:183], v84 offset:4672
	v_add_u32_e32 v101, 0x1000, v100
	v_add_u32_e32 v102, 0x2000, v100
	v_add_u32_e32 v103, 0x3000, v100
	s_waitcnt lgkmcnt(13)
	s_waitcnt lgkmcnt(12)
	v_mfma_f32_16x16x32_bf16 v[2:5], v[6:9], v[104:107], 0
	ds_read_b128 v[184:187], v0 offset:4608
	ds_read_b128 v[188:191], v0 offset:4672
	s_waitcnt lgkmcnt(11)
	s_waitcnt lgkmcnt(10)
	v_mfma_f32_16x16x32_bf16 v[42:45], v[48:51], v[112:115], 0
	ds_read_b128 v[192:195], v84 offset:6912
	ds_read_b128 v[196:199], v84 offset:6976
	ds_read_b128 v[206:209], v0 offset:6912
	ds_read_b128 v[210:213], v0 offset:6976
	v_mfma_f32_16x16x32_bf16 v[2:5], v[14:17], v[108:111], v[2:5]
	s_waitcnt lgkmcnt(13)
	s_waitcnt lgkmcnt(12)
	v_mfma_f32_16x16x32_bf16 v[42:45], v[10:13], v[116:119], v[42:45]
	s_waitcnt lgkmcnt(11)
	v_mfma_f32_16x16x32_bf16 v[52:55], v[6:9], v[120:123], 0
	s_waitcnt lgkmcnt(9)
	v_mfma_f32_16x16x32_bf16 v[60:63], v[48:51], v[128:131], 0
	v_mfma_f32_16x16x32_bf16 v[52:55], v[14:17], v[124:127], v[52:55]
	s_waitcnt lgkmcnt(8)
	v_mfma_f32_16x16x32_bf16 v[60:63], v[10:13], v[132:135], v[60:63]
	s_nop 4
	v_cvt_pk_bf16_f32 v2, v2, v3
	v_cvt_pk_bf16_f32 v3, v4, v5
	global_store_dwordx2 v100, v[2:3], s[8:9]
	v_cvt_pk_bf16_f32 v42, v42, v43
	v_cvt_pk_bf16_f32 v43, v44, v45
	global_store_dwordx2 v100, v[42:43], s[6:7]
	s_waitcnt lgkmcnt(7)
	v_mfma_f32_16x16x32_bf16 v[64:67], v[6:9], v[176:179], 0
	s_waitcnt lgkmcnt(5)
	v_mfma_f32_16x16x32_bf16 v[146:149], v[48:51], v[184:187], 0
	v_mfma_f32_16x16x32_bf16 v[64:67], v[14:17], v[180:183], v[64:67]
	s_waitcnt lgkmcnt(4)
	v_mfma_f32_16x16x32_bf16 v[146:149], v[10:13], v[188:191], v[146:149]
	v_cvt_pk_bf16_f32 v52, v52, v53
	v_cvt_pk_bf16_f32 v53, v54, v55
	global_store_dwordx2 v101, v[52:53], s[8:9]
	v_cvt_pk_bf16_f32 v60, v60, v61
	v_cvt_pk_bf16_f32 v61, v62, v63
	global_store_dwordx2 v101, v[60:61], s[6:7]
	s_waitcnt lgkmcnt(3)
	v_mfma_f32_16x16x32_bf16 v[150:153], v[6:9], v[192:195], 0
	s_waitcnt lgkmcnt(1)
	v_mfma_f32_16x16x32_bf16 v[154:157], v[48:51], v[206:209], 0
	v_mfma_f32_16x16x32_bf16 v[150:153], v[14:17], v[196:199], v[150:153]
	s_waitcnt lgkmcnt(0)
	v_mfma_f32_16x16x32_bf16 v[154:157], v[10:13], v[210:213], v[154:157]
	v_cvt_pk_bf16_f32 v64, v64, v65
	v_cvt_pk_bf16_f32 v65, v66, v67
	global_store_dwordx2 v102, v[64:65], s[8:9]
	v_cvt_pk_bf16_f32 v146, v146, v147
	v_cvt_pk_bf16_f32 v147, v148, v149
	global_store_dwordx2 v102, v[146:147], s[6:7]
	s_and_b64 vcc, exec, s[38:39]
	s_nop 1
	v_cvt_pk_bf16_f32 v150, v150, v151
	v_cvt_pk_bf16_f32 v151, v152, v153
	global_store_dwordx2 v103, v[150:151], s[8:9]
	v_cvt_pk_bf16_f32 v154, v154, v155
	v_cvt_pk_bf16_f32 v155, v156, v157
	global_store_dwordx2 v103, v[154:155], s[6:7]
	s_cbranch_vccnz .LBB0_601
